# dead VALU removed from the attention k-loop; accumulators cleared with 64-bit moves
# baseline (speedup 1.0000x reference)
; template <class Epi, class Sched, bool ALIGN_EPI = false, bool SP2 = false>
; __device__ __forceinline__ void gemm_phase(PG8_LAS unsigned char* lds, const Gemm g, const Sched& S, const Epi& E) {
;     ...
;     for (int a = 0; a < 2; ++a)
; #pragma unroll
;         for (int b = 0; b < 2; ++b)
; #pragma unroll
;             for (int m = 0; m < 4; ++m)
; #pragma unroll
;                 for (int n = 0; n < 2; ++n) acc[a][b][m][n] = (f32x4){0.f, 0.f, 0.f, 0.f};
;     ...
;         for (int t = 0; t < nt; t += 2) {
;             const bool last = (t == nt - 2);
;             const char* a1 = cA + (size_t)(t + 1) * kstep;
;             const char* a2 = last ? nA : cA + (size_t)(t + 2) * kstep; const char* b2 = last ? nB : cB + (size_t)(t + 2) * kstep;
.LBB0_32:
	s_add_u32 s42, s18, 0x100
	s_addc_u32 s43, s19, 0
	s_mov_b32 s55, -2
	s_waitcnt lgkmcnt(0)
	v_mov_b64_e32 v[0:1], 0
	v_mov_b64_e32 v[2:3], 0
	v_mov_b64_e32 v[4:5], 0
	v_mov_b64_e32 v[6:7], 0
	v_mov_b64_e32 v[8:9], 0
	v_mov_b64_e32 v[10:11], 0
	v_mov_b64_e32 v[12:13], 0
	v_mov_b64_e32 v[14:15], 0
	v_mov_b64_e32 v[16:17], 0
	v_mov_b64_e32 v[18:19], 0
	v_mov_b64_e32 v[20:21], 0
	v_mov_b64_e32 v[22:23], 0
	v_mov_b64_e32 v[24:25], 0
	v_mov_b64_e32 v[26:27], 0
	v_mov_b64_e32 v[28:29], 0
	v_mov_b64_e32 v[30:31], 0
	v_mov_b64_e32 v[32:33], 0
	v_mov_b64_e32 v[34:35], 0
	v_mov_b64_e32 v[36:37], 0
	v_mov_b64_e32 v[38:39], 0
	v_mov_b64_e32 v[40:41], 0
	v_mov_b64_e32 v[42:43], 0
	v_mov_b64_e32 v[44:45], 0
	v_mov_b64_e32 v[46:47], 0
	v_mov_b64_e32 v[48:49], 0
	v_mov_b64_e32 v[50:51], 0
	v_mov_b64_e32 v[52:53], 0
	v_mov_b64_e32 v[54:55], 0
	v_mov_b64_e32 v[56:57], 0
	v_mov_b64_e32 v[58:59], 0
	v_mov_b64_e32 v[60:61], 0
	v_mov_b64_e32 v[62:63], 0
	v_mov_b64_e32 v[64:65], 0
	v_mov_b64_e32 v[66:67], 0
	v_mov_b64_e32 v[68:69], 0
	v_mov_b64_e32 v[70:71], 0
	v_mov_b64_e32 v[72:73], 0
	v_mov_b64_e32 v[74:75], 0
	v_mov_b64_e32 v[76:77], 0
	v_mov_b64_e32 v[78:79], 0
	v_mov_b64_e32 v[80:81], 0
	v_mov_b64_e32 v[82:83], 0
	v_mov_b64_e32 v[84:85], 0
	v_mov_b64_e32 v[86:87], 0
	v_mov_b64_e32 v[88:89], 0
	v_mov_b64_e32 v[90:91], 0
	v_mov_b64_e32 v[92:93], 0
	v_mov_b64_e32 v[94:95], 0
	v_mov_b64_e32 v[96:97], 0
	v_mov_b64_e32 v[98:99], 0
	v_mov_b64_e32 v[100:101], 0
	v_mov_b64_e32 v[102:103], 0
	v_mov_b64_e32 v[104:105], 0
	v_mov_b64_e32 v[106:107], 0
	v_mov_b64_e32 v[108:109], 0
	v_mov_b64_e32 v[110:111], 0
	v_mov_b64_e32 v[116:117], 0
	v_mov_b64_e32 v[118:119], 0
	v_mov_b64_e32 v[120:121], 0
	v_mov_b64_e32 v[122:123], 0
	v_mov_b64_e32 v[132:133], 0
	v_mov_b64_e32 v[134:135], 0
	v_mov_b64_e32 v[136:137], 0
	v_mov_b64_e32 v[138:139], 0

; template <class Epi, class Sched, bool ALIGN_EPI = false, bool SP2 = false>
; __device__ __forceinline__ void gemm_phase(PG8_LAS unsigned char* lds, const Gemm g, const Sched& S, const Epi& E) {
;     ...
;         const bool has_next = S.next(ui + 1, nxt);
;         const char* nA = has_next ? (const char*)g.A + (size_t)nxt.pm * tstepA : cA; const char* nB = has_next ? (const char*)g.Bt + (size_t)nxt.pn * tstep : cB;
;         for (int t = 0; t < nt; t += 2) {
;             const bool last = (t == nt - 2);
;             const char* a1 = cA + (size_t)(t + 1) * kstep;
;             const char* a2 = last ? nA : cA + (size_t)(t + 2) * kstep; const char* b2 = last ? nB : cB + (size_t)(t + 2) * kstep;
;     ...
;         for (int a = 0; a < 2; ++a)
; #pragma unroll
;             for (int b = 0; b < 2; ++b)
; #pragma unroll
;                 for (int m = 0; m < 4; ++m)
; #pragma unroll
;                     for (int n = 0; n < 2; ++n) acc[a][b][m][n] = (f32x4){0.f, 0.f, 0.f, 0.f};
.LBB0_76:
	s_ashr_i32 s21, s20, 31
	s_lshl_b64 s[24:25], s[20:21], 19
	s_add_u32 s24, s29, s24
	s_addc_u32 s25, s33, s25
	s_and_b64 s[56:57], s[56:57], exec
	s_cselect_b32 s21, s25, s63
	s_cselect_b32 s77, s24, s62
	s_add_u32 s78, s62, 0x100
	s_addc_u32 s79, s63, 0
	s_mov_b32 s80, -2
	v_mov_b64_e32 v[0:1], 0
	v_mov_b64_e32 v[2:3], 0
	v_mov_b64_e32 v[4:5], 0
	v_mov_b64_e32 v[6:7], 0
	v_mov_b64_e32 v[8:9], 0
	v_mov_b64_e32 v[10:11], 0
	v_mov_b64_e32 v[12:13], 0
	v_mov_b64_e32 v[14:15], 0
	v_mov_b64_e32 v[16:17], 0
	v_mov_b64_e32 v[18:19], 0
	v_mov_b64_e32 v[20:21], 0
	v_mov_b64_e32 v[22:23], 0
	v_mov_b64_e32 v[24:25], 0
	v_mov_b64_e32 v[26:27], 0
	v_mov_b64_e32 v[28:29], 0
	v_mov_b64_e32 v[30:31], 0
	v_mov_b64_e32 v[32:33], 0
	v_mov_b64_e32 v[34:35], 0
	v_mov_b64_e32 v[36:37], 0
	v_mov_b64_e32 v[38:39], 0
	v_mov_b64_e32 v[40:41], 0
	v_mov_b64_e32 v[42:43], 0
	v_mov_b64_e32 v[44:45], 0
	v_mov_b64_e32 v[46:47], 0
	v_mov_b64_e32 v[48:49], 0
	v_mov_b64_e32 v[50:51], 0
	v_mov_b64_e32 v[52:53], 0
	v_mov_b64_e32 v[54:55], 0
	v_mov_b64_e32 v[56:57], 0
	v_mov_b64_e32 v[58:59], 0
	v_mov_b64_e32 v[60:61], 0
	v_mov_b64_e32 v[62:63], 0
	v_mov_b64_e32 v[64:65], 0
	v_mov_b64_e32 v[66:67], 0
	v_mov_b64_e32 v[68:69], 0
	v_mov_b64_e32 v[70:71], 0
	v_mov_b64_e32 v[72:73], 0
	v_mov_b64_e32 v[74:75], 0
	v_mov_b64_e32 v[76:77], 0
	v_mov_b64_e32 v[78:79], 0
	v_mov_b64_e32 v[80:81], 0
	v_mov_b64_e32 v[82:83], 0
	v_mov_b64_e32 v[84:85], 0
	v_mov_b64_e32 v[86:87], 0
	v_mov_b64_e32 v[88:89], 0
	v_mov_b64_e32 v[90:91], 0
	v_mov_b64_e32 v[92:93], 0
	v_mov_b64_e32 v[94:95], 0
	v_mov_b64_e32 v[96:97], 0
	v_mov_b64_e32 v[98:99], 0
	v_mov_b64_e32 v[100:101], 0
	v_mov_b64_e32 v[102:103], 0
	v_mov_b64_e32 v[104:105], 0
	v_mov_b64_e32 v[106:107], 0
	v_mov_b64_e32 v[108:109], 0
	v_mov_b64_e32 v[110:111], 0
	v_mov_b64_e32 v[112:113], 0
	v_mov_b64_e32 v[114:115], 0
	v_mov_b64_e32 v[120:121], 0
	v_mov_b64_e32 v[122:123], 0
	v_mov_b64_e32 v[124:125], 0
	v_mov_b64_e32 v[126:127], 0
	v_mov_b64_e32 v[128:129], 0
	v_mov_b64_e32 v[130:131], 0

; template <class Epi, class Sched, bool ALIGN_EPI = false, bool SP2 = false>
; __device__ __forceinline__ void gemm_phase(PG8_LAS unsigned char* lds, const Gemm g, const Sched& S, const Epi& E) {
;     ...
;         const bool has_next = S.next(ui + 1, nxt);
;         const char* nA = has_next ? (const char*)g.A + (size_t)nxt.pm * tstepA : cA; const char* nB = has_next ? (const char*)g.Bt + (size_t)nxt.pn * tstep : cB;
;         for (int t = 0; t < nt; t += 2) {
;             const bool last = (t == nt - 2);
;             const char* a1 = cA + (size_t)(t + 1) * kstep;
;             const char* a2 = last ? nA : cA + (size_t)(t + 2) * kstep; const char* b2 = last ? nB : cB + (size_t)(t + 2) * kstep;
;             const char* a3 = a2 + kstep; const char* b3 = b2 + kstep;
;     ...
;         for (int a = 0; a < 2; ++a)
; #pragma unroll
;             for (int b = 0; b < 2; ++b)
; #pragma unroll
;                 for (int m = 0; m < 4; ++m)
; #pragma unroll
;                     for (int n = 0; n < 2; ++n) acc[a][b][m][n] = (f32x4){0.f, 0.f, 0.f, 0.f};
.LBB0_127:
	s_ashr_i32 s15, s14, 31
	s_lshl_b64 s[16:17], s[14:15], 19
	s_add_u32 s16, s2, s16
	s_addc_u32 s17, s28, s17
	s_and_b64 s[18:19], s[40:41], exec
	s_cselect_b32 s15, s17, s23
	s_cselect_b32 s53, s16, s22
	s_ashr_i32 s13, s12, 31
	s_lshl_b64 s[18:19], s[12:13], 19
	s_add_u32 s18, s29, s18
	s_addc_u32 s19, s33, s19
	s_and_b64 s[24:25], s[40:41], exec
	s_cselect_b32 s13, s19, s21
	s_cselect_b32 s54, s18, s20
	s_add_u32 s55, s20, 0x100
	s_addc_u32 s56, s21, 0
	s_add_u32 s20, s22, 0x40080
	s_addc_u32 s21, s23, 0
	s_mov_b32 s57, -2
	s_waitcnt lgkmcnt(0)
	v_mov_b64_e32 v[0:1], 0
	v_mov_b64_e32 v[2:3], 0
	v_mov_b64_e32 v[4:5], 0
	v_mov_b64_e32 v[6:7], 0
	v_mov_b64_e32 v[8:9], 0
	v_mov_b64_e32 v[10:11], 0
	v_mov_b64_e32 v[12:13], 0
	v_mov_b64_e32 v[14:15], 0
	v_mov_b64_e32 v[16:17], 0
	v_mov_b64_e32 v[18:19], 0
	v_mov_b64_e32 v[20:21], 0
	v_mov_b64_e32 v[22:23], 0
	v_mov_b64_e32 v[24:25], 0
	v_mov_b64_e32 v[26:27], 0
	v_mov_b64_e32 v[28:29], 0
	v_mov_b64_e32 v[30:31], 0
	v_mov_b64_e32 v[32:33], 0
	v_mov_b64_e32 v[34:35], 0
	v_mov_b64_e32 v[36:37], 0
	v_mov_b64_e32 v[38:39], 0
	v_mov_b64_e32 v[40:41], 0
	v_mov_b64_e32 v[42:43], 0
	v_mov_b64_e32 v[44:45], 0
	v_mov_b64_e32 v[46:47], 0
	v_mov_b64_e32 v[48:49], 0
	v_mov_b64_e32 v[50:51], 0
	v_mov_b64_e32 v[52:53], 0
	v_mov_b64_e32 v[54:55], 0
	v_mov_b64_e32 v[56:57], 0
	v_mov_b64_e32 v[58:59], 0
	v_mov_b64_e32 v[60:61], 0
	v_mov_b64_e32 v[62:63], 0
	v_mov_b64_e32 v[64:65], 0
	v_mov_b64_e32 v[66:67], 0
	v_mov_b64_e32 v[68:69], 0
	v_mov_b64_e32 v[70:71], 0
	v_mov_b64_e32 v[72:73], 0
	v_mov_b64_e32 v[74:75], 0
	v_mov_b64_e32 v[76:77], 0
	v_mov_b64_e32 v[78:79], 0
	v_mov_b64_e32 v[80:81], 0
	v_mov_b64_e32 v[82:83], 0
	v_mov_b64_e32 v[84:85], 0
	v_mov_b64_e32 v[86:87], 0
	v_mov_b64_e32 v[88:89], 0
	v_mov_b64_e32 v[90:91], 0
	v_mov_b64_e32 v[92:93], 0
	v_mov_b64_e32 v[94:95], 0
	v_mov_b64_e32 v[96:97], 0
	v_mov_b64_e32 v[98:99], 0
	v_mov_b64_e32 v[100:101], 0
	v_mov_b64_e32 v[102:103], 0
	v_mov_b64_e32 v[104:105], 0
	v_mov_b64_e32 v[106:107], 0
	v_mov_b64_e32 v[108:109], 0
	v_mov_b64_e32 v[110:111], 0
	v_mov_b64_e32 v[116:117], 0
	v_mov_b64_e32 v[118:119], 0
	v_mov_b64_e32 v[120:121], 0
	v_mov_b64_e32 v[122:123], 0
	v_mov_b64_e32 v[132:133], 0
	v_mov_b64_e32 v[134:135], 0
	v_mov_b64_e32 v[136:137], 0
	v_mov_b64_e32 v[138:139], 0

; #define LAS __attribute__((address_space(3)))
; __device__ __forceinline__ void mixer_unit(LAS unsigned char* lds, int unit, const bf16* P, bf16* Y, const float* conv_w, const float* sgu_norm, const float* sgu_w, const float* sgu_b, int tid, int wave, int lane) {
;     ...
;         for (int k0 = t0 + 32;; k0 -= 32) {
;             const bool doA = actA && (k0 <= t0);
;             f32x16 zB = {}, zA = {};
;             if (actB) {
; #pragma unroll
;                 for (int ks = 0; ks < 4; ++ks) zB = __builtin_amdgcn_mfma_f32_32x32x16_bf16(kfn[ks], Qs[(4 + ks) * 64 + lane], zB, 0, 0, 0); }
;             if (doA) {
; #pragma unroll
;                 for (int ks = 0; ks < 4; ++ks) zA = __builtin_amdgcn_mfma_f32_32x32x16_bf16(kfn[ks], Qs[ks * 64 + lane], zA, 0, 0, 0); }
; #pragma unroll
;             for (int i = 0; i < 4; ++i) { const int key = (lane >> 3) + 8 * i, c = lane & 7; *(LAS v4u*)(Vr + key * 96 + 8 * c) = vvn[i]; }
; #pragma unroll
;             for (int ks = 0; ks < 4; ++ks) kfn[ks] = kf2[ks];
; #pragma unroll
;             for (int i = 0; i < 4; ++i) vvn[i] = vv2[i];
;             if (k0 >= 64) { const bf16* kp = P + (size_t)(k0 - 64 + pr) * NIN + 1792 + hd * 64 + 8 * h;
; #pragma unroll
;                 for (int ks = 0; ks < 4; ++ks) kf2[ks] = *(const __attribute__((address_space(1))) bf16x8*)(kp + 16 * ks);
; #pragma unroll
;                 for (int i = 0; i < 4; ++i) vv2[i] = *(const __attribute__((address_space(1))) v4u*)(P + (size_t)(k0 - 64 + (lane >> 3) + 8 * i) * NIN + 2304 + hd * 64 + 8 * (lane & 7)); }
.LBB0_172:
	s_waitcnt vmcnt(4)
	v_mov_b64_e32 v[162:163], v[142:143]
	v_mov_b64_e32 v[166:167], v[138:139]
	v_mov_b64_e32 v[170:171], v[134:135]
	v_mov_b64_e32 v[174:175], v[130:131]
	s_waitcnt vmcnt(0)
	v_mov_b64_e32 v[178:179], v[158:159]
	v_mov_b64_e32 v[182:183], v[154:155]
	v_mov_b64_e32 v[186:187], v[150:151]
	v_mov_b64_e32 v[190:191], v[146:147]
	v_cndmask_b32_e64 v65, 0, 1, s[6:7]
	v_mov_b64_e32 v[160:161], v[140:141]
	v_mov_b64_e32 v[164:165], v[136:137]
	v_mov_b64_e32 v[168:169], v[132:133]
	v_mov_b64_e32 v[172:173], v[128:129]
	v_mov_b64_e32 v[176:177], v[156:157]
	v_mov_b64_e32 v[180:181], v[152:153]
	v_mov_b64_e32 v[184:185], v[148:149]
	v_mov_b64_e32 v[188:189], v[144:145]
	v_cmp_ne_u32_e64 s[42:43], 1, v65
	s_andn2_b64 vcc, exec, s[6:7]
	s_cbranch_vccnz .LBB0_174
	ds_read_b128 v[64:67], v242 offset:53248
	ds_read_b128 v[68:71], v242 offset:54272
	ds_read_b128 v[72:75], v242 offset:55296
	ds_read_b128 v[76:79], v242 offset:56320
	s_waitcnt lgkmcnt(3)
	v_mfma_f32_32x32x16_bf16 v[80:95], v[124:127], v[64:67], 0
	s_waitcnt lgkmcnt(2)
	v_mfma_f32_32x32x16_bf16 v[80:95], v[116:119], v[68:71], v[80:95]
	s_waitcnt lgkmcnt(1)
	v_mfma_f32_32x32x16_bf16 v[80:95], v[120:123], v[72:75], v[80:95]
	s_waitcnt lgkmcnt(0)
	v_mfma_f32_32x32x16_bf16 v[80:95], v[112:115], v[76:79], v[80:95]
.LBB0_174:
	s_sub_i32 s10, s5, 32
	s_cmp_le_i32 s10, s28
	s_cselect_b64 s[0:1], -1, 0
	s_and_b64 s[0:1], s[8:9], s[0:1]
	v_cndmask_b32_e64 v65, 0, 1, s[0:1]
	v_cmp_ne_u32_e64 s[40:41], 1, v65
	s_andn2_b64 vcc, exec, s[0:1]
	s_cbranch_vccnz .LBB0_176
	ds_read_b128 v[64:67], v242 offset:49152
	ds_read_b128 v[248:251], v242 offset:50176
	s_waitcnt lgkmcnt(1)
	v_mfma_f32_32x32x16_bf16 v[64:79], v[124:127], v[64:67], 0
	ds_read_b128 v[124:127], v242 offset:51200
	s_waitcnt lgkmcnt(1)
	v_mfma_f32_32x32x16_bf16 v[64:79], v[116:119], v[248:251], v[64:79]
	ds_read_b128 v[116:119], v242 offset:52224
	s_waitcnt lgkmcnt(1)
	v_mfma_f32_32x32x16_bf16 v[64:79], v[120:123], v[124:127], v[64:79]
	s_waitcnt lgkmcnt(0)
	v_mfma_f32_32x32x16_bf16 v[64:79], v[112:115], v[116:119], v[64:79]
.LBB0_176:
	s_cmpk_lt_i32 s5, 0x60
	s_cbranch_scc0 .Latt_noresto
	v_mov_b64_e32 v[144:145], v[188:189]
	v_mov_b64_e32 v[148:149], v[184:185]
	v_mov_b64_e32 v[152:153], v[180:181]
	v_mov_b64_e32 v[156:157], v[176:177]
	v_mov_b64_e32 v[128:129], v[172:173]
	v_mov_b64_e32 v[132:133], v[168:169]
	v_mov_b64_e32 v[136:137], v[164:165]
	v_mov_b64_e32 v[140:141], v[160:161]
	v_mov_b64_e32 v[146:147], v[190:191]
	v_mov_b64_e32 v[150:151], v[186:187]
	v_mov_b64_e32 v[154:155], v[182:183]
	v_mov_b64_e32 v[158:159], v[178:179]
	v_mov_b64_e32 v[130:131], v[174:175]
	v_mov_b64_e32 v[134:135], v[170:171]
	v_mov_b64_e32 v[138:139], v[166:167]
	v_mov_b64_e32 v[142:143], v[162:163]
.Latt_noresto:
	ds_write_b128 v243, v[96:99]
	ds_write_b128 v243, v[100:103] offset:1536
	ds_write_b128 v243, v[104:107] offset:3072
	ds_write_b128 v243, v[108:111] offset:4608
	s_cmpk_lt_i32 s5, 0x60
	s_cbranch_scc0 .LBB0_182
	s_and_b64 vcc, exec, s[42:43]
	s_mov_b64 s[6:7], 0
	s_cbranch_vccz .LBB0_183

; template <class Epi, class Sched, bool ALIGN_EPI = false, bool SP2 = false>
; __device__ __forceinline__ void gemm_phase(PG8_LAS unsigned char* lds, const Gemm g, const Sched& S, const Epi& E) {
;     ...
;     for (int a = 0; a < 2; ++a)
; #pragma unroll
;         for (int b = 0; b < 2; ++b)
; #pragma unroll
;             for (int m = 0; m < 4; ++m)
; #pragma unroll
;                 for (int n = 0; n < 2; ++n) acc[a][b][m][n] = (f32x4){0.f, 0.f, 0.f, 0.f};
;     ...
;         for (int t = 0; t < nt; t += 2) {
;             const bool last = (t == nt - 2);
;             const char* a1 = cA + (size_t)(t + 1) * kstep;
;             const char* a2 = last ? nA : cA + (size_t)(t + 2) * kstep; const char* b2 = last ? nB : cB + (size_t)(t + 2) * kstep;
.LBB0_303:
	s_ashr_i32 s15, s14, 31
	s_lshl_b64 s[16:17], s[14:15], 19
	s_add_u32 s16, s5, s16
	s_addc_u32 s17, s28, s17
	s_and_b64 s[18:19], s[40:41], exec
	s_cselect_b32 s15, s17, s23
	s_cselect_b32 s52, s16, s22
	s_ashr_i32 s13, s12, 31
	s_lshl_b64 s[18:19], s[12:13], 19
	s_add_u32 s18, s29, s18
	s_addc_u32 s19, s33, s19
	s_and_b64 s[24:25], s[40:41], exec
	s_cselect_b32 s13, s19, s21
	s_cselect_b32 s53, s18, s20
	s_add_u32 s54, s20, 0x100
	s_addc_u32 s55, s21, 0
	s_add_u32 s20, s22, 0x40080
	s_addc_u32 s21, s23, 0
	s_mov_b32 s56, -2
	v_mov_b64_e32 v[0:1], 0
	v_mov_b64_e32 v[2:3], 0
	v_mov_b64_e32 v[4:5], 0
	v_mov_b64_e32 v[6:7], 0
	v_mov_b64_e32 v[8:9], 0
	v_mov_b64_e32 v[10:11], 0
	v_mov_b64_e32 v[12:13], 0
	v_mov_b64_e32 v[14:15], 0
	v_mov_b64_e32 v[16:17], 0
	v_mov_b64_e32 v[18:19], 0
	v_mov_b64_e32 v[20:21], 0
	v_mov_b64_e32 v[22:23], 0
	v_mov_b64_e32 v[24:25], 0
	v_mov_b64_e32 v[26:27], 0
	v_mov_b64_e32 v[28:29], 0
	v_mov_b64_e32 v[30:31], 0
	v_mov_b64_e32 v[32:33], 0
	v_mov_b64_e32 v[34:35], 0
	v_mov_b64_e32 v[36:37], 0
	v_mov_b64_e32 v[38:39], 0
	v_mov_b64_e32 v[40:41], 0
	v_mov_b64_e32 v[42:43], 0
	v_mov_b64_e32 v[44:45], 0
	v_mov_b64_e32 v[46:47], 0
	v_mov_b64_e32 v[48:49], 0
	v_mov_b64_e32 v[50:51], 0
	v_mov_b64_e32 v[52:53], 0
	v_mov_b64_e32 v[54:55], 0
	v_mov_b64_e32 v[56:57], 0
	v_mov_b64_e32 v[58:59], 0
	v_mov_b64_e32 v[60:61], 0
	v_mov_b64_e32 v[62:63], 0
	v_mov_b64_e32 v[64:65], 0
	v_mov_b64_e32 v[66:67], 0
	v_mov_b64_e32 v[68:69], 0
	v_mov_b64_e32 v[70:71], 0
	v_mov_b64_e32 v[72:73], 0
	v_mov_b64_e32 v[74:75], 0
	v_mov_b64_e32 v[76:77], 0
	v_mov_b64_e32 v[78:79], 0
	v_mov_b64_e32 v[80:81], 0
	v_mov_b64_e32 v[82:83], 0
	v_mov_b64_e32 v[84:85], 0
	v_mov_b64_e32 v[86:87], 0
	v_mov_b64_e32 v[88:89], 0
	v_mov_b64_e32 v[90:91], 0
	v_mov_b64_e32 v[92:93], 0
	v_mov_b64_e32 v[94:95], 0
	v_mov_b64_e32 v[96:97], 0
	v_mov_b64_e32 v[98:99], 0
	v_mov_b64_e32 v[100:101], 0
	v_mov_b64_e32 v[102:103], 0
	v_mov_b64_e32 v[104:105], 0
	v_mov_b64_e32 v[106:107], 0
	v_mov_b64_e32 v[108:109], 0
	v_mov_b64_e32 v[110:111], 0
	v_mov_b64_e32 v[112:113], 0
	v_mov_b64_e32 v[114:115], 0
	v_mov_b64_e32 v[116:117], 0
	v_mov_b64_e32 v[118:119], 0
	v_mov_b64_e32 v[120:121], 0
	v_mov_b64_e32 v[122:123], 0
	v_mov_b64_e32 v[124:125], 0
	v_mov_b64_e32 v[126:127], 0
